# S5 scan input tile XOR-swizzled by 4-row group (LDS bank conflicts of the projection writes 4-way -> 2-way); on top of the matrix-core forward substitution
# baseline (speedup 1.0000x reference)
.LBB0_188:
	s_or_b64 exec, exec, s[0:1]
	s_movk_i32 s0, 0x200
	v_cmp_gt_u32_e64 s[0:1], s0, v162
	v_and_b32_e32 v141, -4, v162
	s_waitcnt lgkmcnt(0)
	v_and_b32_e32 v0, 3, v162
	v_writelane_b32 v252, s0, 30
	v_lshlrev_b32_e32 v2, 2, v0
	v_bfe_u32 v4, v162, 2, 4
	v_writelane_b32 v252, s1, 31
	v_cmp_lt_u32_e64 s[0:1], 63, v162
	v_bitop3_b32 v5, v2, v139, 15 bitop3:0x78
	v_lshlrev_b32_e32 v76, 5, v0
	v_writelane_b32 v252, s0, 32
	v_lshlrev_b32_e32 v17, 6, v0
	v_lshlrev_b32_e32 v9, 4, v5
	v_writelane_b32 v252, s1, 33
	v_cmp_gt_u32_e64 s[0:1], 2, v161
	v_bitop3_b32 v5, v2, v4, 1 bitop3:0x36
	v_lshlrev_b32_e32 v21, 11, v0
	v_writelane_b32 v252, s0, 34
	v_and_b32_e32 v0, 0xf0, v139
	v_lshlrev_b32_e32 v104, 2, v136
	v_writelane_b32 v252, s1, 35
	v_cmp_gt_u32_e64 s[0:1], 4, v161
	v_lshlrev_b32_e32 v11, 4, v5
	v_bitop3_b32 v5, v2, v4, 2 bitop3:0x36
	v_writelane_b32 v252, s0, 36
	v_bitop3_b32 v2, v2, v4, 3 bitop3:0x36
	v_or_b32_e32 v4, v0, v98
	v_writelane_b32 v252, s1, 37
	v_cmp_gt_u32_e64 s[0:1], 8, v161
	v_lshlrev_b32_e32 v151, 8, v98
	v_or_b32_e32 v0, v104, v0
	v_writelane_b32 v252, s0, 38
	v_lshlrev_b32_e32 v13, 4, v5
	v_bitop3_b32 v5, v136, v162, 15 bitop3:0x78
	v_writelane_b32 v252, s1, 39
	v_cmp_gt_u32_e64 s[0:1], 16, v161
	v_lshlrev_b32_e32 v143, 4, v5
	v_bitop3_b32 v5, v136, v98, 4 bitop3:0x36
	v_writelane_b32 v252, s0, 40
	v_lshlrev_b32_e32 v145, 4, v5
	v_bitop3_b32 v5, v136, v98, 8 bitop3:0x36
	v_writelane_b32 v252, s1, 41
	s_movk_i32 s0, 0xfc
	v_mad_u32_u24 v3, v139, s0, v141
	s_movk_i32 s0, 0x80
	v_cmp_gt_u32_e64 s[6:7], s0, v162
	s_movk_i32 s0, 0x7f
	v_cmp_lt_u32_e64 s[0:1], s0, v162
	v_lshlrev_b32_e32 v147, 4, v5
	v_bitop3_b32 v5, v136, v98, 12 bitop3:0x36
	v_writelane_b32 v252, s0, 42
	v_lshlrev_b32_e32 v4, 8, v4
	v_lshlrev_b32_e32 v149, 4, v5
	v_writelane_b32 v252, s1, 43
	s_movk_i32 s0, 0xbf
	v_cmp_lt_u32_e64 s[0:1], s0, v162
	v_or_b32_e32 v144, v4, v143
	v_or_b32_e32 v146, v4, v145
	v_writelane_b32 v252, s0, 44
	v_or_b32_e32 v148, v4, v147
	v_or_b32_e32 v150, v4, v149
	v_writelane_b32 v252, s1, 45
	s_movk_i32 s0, 0xff04
	v_mad_i32_i24 v152, v98, s0, v151
	v_cmp_gt_u32_e64 s[0:1], v0, v98
	v_or_b32_e32 v4, 1, v0
	v_or_b32_e32 v5, 2, v0
	v_writelane_b32 v252, s0, 46
	v_or_b32_e32 v6, 3, v0
	v_or_b32_e32 v7, 16, v98
	v_writelane_b32 v252, s1, 47
	v_cmp_lt_u32_e64 s[0:1], v0, v98
	v_lshlrev_b32_e32 v153, 2, v0
	v_lshl_or_b32 v10, v0, 6, v98
	v_writelane_b32 v252, s0, 48
	v_lshl_add_u32 v159, v0, 8, v152
	v_lshl_or_b32 v12, v4, 6, v98
	v_writelane_b32 v252, s1, 49
	v_cmp_ge_u32_e64 s[0:1], v0, v98
	v_lshl_add_u32 v165, v4, 8, v152
	v_lshl_or_b32 v14, v5, 6, v98
	v_writelane_b32 v252, s0, 50
	v_lshl_or_b32 v16, v6, 6, v98
	v_lshl_add_u32 v166, v5, 8, v152
	v_writelane_b32 v252, s1, 51
	v_cmp_lt_u32_e64 s[0:1], v4, v98
	v_lshl_add_u32 v167, v6, 8, v152
	v_mov_b32_e32 v1, 0
	v_writelane_b32 v252, s0, 52
	v_and_b32_e32 v24, 0xffffffc, v101
	v_mov_b32_e32 v25, v1
	v_writelane_b32 v252, s1, 53
	v_cmp_gt_u32_e64 s[0:1], v5, v98
	v_not_b32_e32 v190, 63
	v_and_b32_e32 v20, 8, v97
	v_writelane_b32 v252, s0, 54
	v_lshl_add_u64 v[80:81], s[42:43], 0, v[24:25]
	v_bitop3_b32 v24, v162, 63, v190 bitop3:0xe0
	v_writelane_b32 v252, s1, 55
	v_cmp_lt_u32_e64 s[0:1], v5, v98
	v_add_u32_e32 v191, 0xffd80000, v24
	v_lshlrev_b64 v[24:25], 2, v[24:25]
	v_writelane_b32 v252, s0, 56
	s_movk_i32 s85, 0x1400
	v_lshlrev_b32_e32 v106, 5, v160
	v_writelane_b32 v252, s1, 57
	v_cmp_gt_u32_e64 s[0:1], v6, v98
	v_and_b32_e32 v23, 1, v162
	v_lshl_add_u64 v[82:83], s[40:41], 0, v[24:25]
	v_writelane_b32 v252, s0, 58
	v_lshl_add_u64 v[86:87], s[38:39], 0, v[24:25]
	v_lshlrev_b32_e32 v107, 4, v160
	v_writelane_b32 v252, s1, 59
	v_cmp_lt_u32_e64 s[0:1], v6, v98
	v_readlane_b32 s12, v251, 24
	v_mov_b32_e32 v163, v1
	v_writelane_b32 v252, s0, 60
	v_or_b32_e32 v74, v107, v98
	v_readlane_b32 s13, v251, 25
	v_writelane_b32 v252, s1, 61
	v_cmp_gt_u32_e64 s[0:1], v0, v7
	v_readlane_b32 s14, v251, 26
	v_readlane_b32 s15, v251, 27
	v_writelane_b32 v252, s0, 62
	v_readlane_b32 s16, v251, 28
	v_readlane_b32 s17, v251, 29
	v_writelane_b32 v252, s1, 63
	v_cmp_lt_u32_e64 s[0:1], v0, v7
	v_readlane_b32 s18, v251, 30
	v_readlane_b32 s19, v251, 31
	v_writelane_b32 v250, s0, 0
	v_readlane_b32 s20, v251, 32
	v_readlane_b32 s21, v251, 33
	v_writelane_b32 v250, s1, 1
	v_cmp_ge_u32_e64 s[0:1], v0, v7
	v_readlane_b32 s22, v251, 34
	v_readlane_b32 s23, v251, 35
	v_writelane_b32 v250, s0, 2
	v_readlane_b32 s24, v251, 36
	v_readlane_b32 s25, v251, 37
	v_writelane_b32 v250, s1, 3
	v_cmp_lt_u32_e64 s[0:1], v4, v7
	v_readlane_b32 s26, v251, 38
	v_readlane_b32 s27, v251, 39
	v_writelane_b32 v250, s0, 4
	v_mov_b32_e32 v75, v1
	v_lshlrev_b32_e32 v72, 3, v136
	v_writelane_b32 v250, s1, 5
	v_cmp_gt_u32_e64 s[0:1], v5, v7
	v_lshlrev_b32_e32 v105, 10, v160
	v_lshl_add_u64 v[90:91], v[162:163], 2, s[12:13]
	v_writelane_b32 v250, s0, 6
	v_lshlrev_b32_e32 v140, 2, v161
	v_or_b32_e32 v19, 0x6000, v139
	v_writelane_b32 v250, s1, 7
	v_cmp_lt_u32_e64 s[0:1], v5, v7
	v_lshlrev_b32_e32 v77, 6, v98
	v_lshl_or_b32 v26, v161, 4, v105
	v_writelane_b32 v250, s0, 8
	v_mov_b32_e32 v27, v1
	v_lshlrev_b32_e32 v18, 8, v139
	v_writelane_b32 v250, s1, 9
	v_cmp_gt_u32_e64 s[0:1], v6, v7
	v_lshlrev_b32_e32 v8, 7, v139
	v_lshlrev_b32_e32 v15, 4, v2
	v_writelane_b32 v250, s0, 10
	v_or_b32_e32 v2, v19, v21
	v_lshlrev_b32_e32 v99, 1, v162
	v_writelane_b32 v250, s1, 11
	v_cmp_lt_u32_e64 s[0:1], v6, v7
	v_or_b32_e32 v7, 32, v98
	v_mul_u32_u24_e32 v29, 0x110, v74
	v_writelane_b32 v250, s0, 12
	v_mul_u32_u24_e32 v30, 0x50, v74
	v_mul_u32_u24_e32 v31, 0x50, v98
	v_writelane_b32 v250, s1, 13
	v_cmp_gt_u32_e64 s[0:1], v0, v7
	v_lshlrev_b32_e32 v32, 11, v136
	v_or_b32_e32 v33, v77, v104
	v_writelane_b32 v250, s0, 14
	v_add_u32_e32 v22, v21, v19
	v_lshl_or_b32 v19, v160, 8, v140
	v_writelane_b32 v250, s1, 15
	v_cmp_lt_u32_e64 s[0:1], v0, v7
	v_lshlrev_b64 v[26:27], 2, v[26:27]
	s_mov_b64 s[60:61], s[86:87]
	v_writelane_b32 v250, s0, 16
	s_mov_b32 s59, s84
	v_cmp_gt_u32_e64 s[10:11], 64, v162
	v_writelane_b32 v250, s1, 17
	v_cmp_ge_u32_e64 s[0:1], v0, v7
	s_mov_b32 s9, 0
	v_cmp_eq_u32_e64 s[66:67], 0, v161
	v_writelane_b32 v250, s0, 18
	v_cmp_gt_u32_e64 s[4:5], 32, v161
	v_add_u32_e32 v142, -3, v139
	v_writelane_b32 v250, s1, 19
	v_cmp_lt_u32_e64 s[0:1], v4, v7
	v_lshlrev_b32_e32 v155, 2, v10
	v_lshlrev_b32_e32 v156, 2, v12
	v_writelane_b32 v250, s0, 20
	v_lshlrev_b32_e32 v157, 2, v14
	v_lshlrev_b32_e32 v158, 2, v16
	v_writelane_b32 v250, s1, 21
	v_cmp_gt_u32_e64 s[0:1], v5, v7
	v_cmp_eq_u32_e64 s[94:95], 1, v23
	v_mov_b32_e32 v73, v1
	v_writelane_b32 v250, s0, 22
	v_add_u32_e32 v103, 0xffffff00, v162
	v_and_b32_e32 v189, 0xffffffc0, v162
	v_writelane_b32 v250, s1, 23
	v_cmp_lt_u32_e64 s[0:1], v5, v7
	v_add_u32_e32 v192, 0x800, v19
	v_lshl_add_u64 v[84:85], s[44:45], 0, v[26:27]
	v_writelane_b32 v250, s0, 24
	v_lshl_add_u64 v[88:89], s[46:47], 0, v[26:27]
	v_lshlrev_b64 v[92:93], 8, v[162:163]
	v_writelane_b32 v250, s1, 25
	v_cmp_gt_u32_e64 s[0:1], v6, v7
	v_add_u32_e32 v193, 0xc400, v99
	v_mov_b32_e32 v194, 0x10810
	v_writelane_b32 v250, s0, 26
	s_mov_b32 s86, 0x3fb8aa3b
	s_mov_b32 s87, 0xc2ce8ed0
	v_writelane_b32 v250, s1, 27
	v_cmp_lt_u32_e64 s[0:1], v6, v7
	v_or_b32_e32 v7, 48, v98
	s_mov_b32 s88, 0x42b17218
	v_writelane_b32 v250, s0, 28
	s_mov_b32 s37, 0x7f800000
	s_brev_b32 s90, 18
	v_writelane_b32 v250, s1, 29
	v_cmp_gt_u32_e64 s[0:1], v0, v7
	s_mov_b32 s68, 0xfe5163ab
	s_mov_b32 s89, 0x3c439041
	v_writelane_b32 v250, s0, 30
	s_mov_b32 s52, 0xdb629599
	s_mov_b32 s53, 0xf534ddc0
	v_writelane_b32 v250, s1, 31
	v_cmp_lt_u32_e64 s[0:1], v0, v7
	s_mov_b32 s54, 0xfc2757d1
	s_mov_b32 s55, 0x4e441529
	v_writelane_b32 v250, s0, 32
	s_mov_b32 s56, 0xa2f9836e
	s_mov_b32 s57, 0x3fc90fda
	v_writelane_b32 v250, s1, 33
	v_cmp_ge_u32_e64 s[0:1], v0, v7
	v_and_b32_e32 v0, 0x3f8, v162
	s_mov_b32 s3, 0x3f22f983
	v_writelane_b32 v250, s0, 34
	s_mov_b32 s84, 0xbfc90fda
	v_mov_b32_e32 v195, 0x3c0881c4
	v_writelane_b32 v250, s1, 35
	v_cmp_lt_u32_e64 s[0:1], v4, v7
	v_add_u32_e32 v4, 0xffffff80, v0
	v_mov_b32_e32 v196, 0xbab64f3b
	v_writelane_b32 v250, s0, 36
	s_brev_b32 s58, 1
	s_movk_i32 s91, 0x1f8
	v_writelane_b32 v250, s1, 37
	v_cmp_gt_u32_e64 s[0:1], v5, v7
	s_mov_b64 s[34:35], 0x400
	v_mov_b32_e32 v197, 0x3ecc95a3
	v_writelane_b32 v250, s0, 38
	v_lshlrev_b32_e32 v110, 1, v8
	v_lshlrev_b32_e32 v198, 1, v2
	v_writelane_b32 v250, s1, 39
	v_cmp_lt_u32_e64 s[0:1], v5, v7
	v_lshlrev_b32_e32 v5, 1, v219
	v_lshl_or_b32 v168, v4, 1, v5
	v_writelane_b32 v250, s0, 40
	v_lshl_or_b32 v184, v0, 1, v5
	v_or_b32_e32 v0, v106, v98
	v_writelane_b32 v250, s1, 41
	v_cmp_gt_u32_e64 s[0:1], v6, v7
	v_lshrrev_b32_e32 v185, 1, v0
	v_and_b32_e32 v0, 48, v162
	v_writelane_b32 v250, s0, 42
	v_lshl_add_u64 v[78:79], s[12:13], 0, v[0:1]
	v_readlane_b32 s12, v251, 8
	v_writelane_b32 v250, s1, 43
	v_cmp_lt_u32_e64 s[0:1], v6, v7
	v_xor_b32_e32 v6, 8, v4
	v_lshl_or_b32 v169, v6, 1, v5
	v_xor_b32_e32 v6, 16, v4
	v_lshl_or_b32 v170, v6, 1, v5
	v_xor_b32_e32 v6, 24, v4
	v_lshl_or_b32 v171, v6, 1, v5
	v_xor_b32_e32 v6, 32, v4
	v_lshl_or_b32 v172, v6, 1, v5
	v_xor_b32_e32 v6, 40, v4
	v_lshl_or_b32 v173, v6, 1, v5
	v_xor_b32_e32 v6, 48, v4
	v_lshl_or_b32 v174, v6, 1, v5
	v_xor_b32_e32 v6, 56, v4
	v_lshl_or_b32 v175, v6, 1, v5
	v_xor_b32_e32 v6, 64, v4
	v_lshl_or_b32 v176, v6, 1, v5
	v_xor_b32_e32 v6, 0x48, v4
	v_lshl_or_b32 v177, v6, 1, v5
	v_xor_b32_e32 v6, 0x50, v4
	v_lshl_or_b32 v178, v6, 1, v5
	v_xor_b32_e32 v6, 0x58, v4
	v_lshl_or_b32 v179, v6, 1, v5
	v_xor_b32_e32 v6, 0x60, v4
	v_lshl_or_b32 v180, v6, 1, v5
	v_xor_b32_e32 v6, 0x68, v4
	v_lshl_or_b32 v181, v6, 1, v5
	v_xor_b32_e32 v6, 0x70, v4
	v_xor_b32_e32 v4, 0x78, v4
	v_writelane_b32 v250, s0, 44
	v_lshl_or_b32 v183, v4, 1, v5
	v_lshlrev_b32_e32 v4, 7, v160
	v_writelane_b32 v250, s1, 45
	s_movk_i32 s0, 0x50
	v_lshl_or_b32 v28, v98, 2, v4
	v_lshlrev_b32_e32 v4, 1, v20
	v_mad_u32_u24 v187, v100, s0, v4
	v_mad_u64_u32 v[24:25], s[0:1], v100, s85, 0
	v_lshl_or_b32 v24, v23, 4, v24
	v_lshl_add_u64 v[24:25], s[28:29], 0, v[24:25]
	s_mov_b64 s[0:1], 0x50000
	v_sub_u32_e32 v4, 0x9ff, v162
	v_lshl_add_u64 v[94:95], v[24:25], 0, s[0:1]
	v_lshlrev_b64 v[24:25], 10, v[74:75]
	v_lshrrev_b32_e32 v4, 8, v4
	v_or_b32_e32 v24, v24, v72
	v_readlane_b32 s13, v251, 9
	v_lshl_or_b32 v182, v6, 1, v5
	v_add_u32_e32 v5, 4, v4
	v_lshl_add_u64 v[24:25], s[12:13], 0, v[24:25]
	v_or_b32_e32 v186, 8, v185
	v_and_b32_e32 v188, 28, v5
	v_mov_b32_e32 v5, v4
	v_mov_b32_e32 v6, v4
	v_mov_b32_e32 v7, v4
	v_lshl_add_u64 v[108:109], v[24:25], 0, 4
	v_lshlrev_b32_e32 v199, 1, v22
	v_add_u32_e32 v200, v17, v18
	v_lshlrev_b32_e32 v112, 1, v10
	v_lshlrev_b32_e32 v114, 1, v12
	v_lshlrev_b32_e32 v116, 1, v14
	v_lshlrev_b32_e32 v118, 1, v16
	v_mov_b32_e32 v201, 0xc108
	v_lshlrev_b32_e32 v202, 2, v33
	v_lshlrev_b32_e32 v120, 1, v20
	v_add_u32_e32 v203, v0, v31
	v_add_u32_e32 v204, v28, v32
	v_bfe_u32 v253, v162, 4, 2
	v_lshlrev_b32_e32 v253, 7, v253
	v_xor_b32_e32 v204, v204, v253
	v_add_u32_e32 v205, v29, v0
	v_add_u32_e32 v206, v72, v30
	v_mov_b32_e32 v207, 0x7f800000
	v_not_b32_e32 v208, 31
	v_mov_b32_e32 v209, 0x7fc00000
	v_mbcnt_hi_u32_b32 v154, -1, v230
	v_add_u32_e32 v210, v3, v9
	v_add_u32_e32 v211, v3, v11
	v_add_u32_e32 v212, v3, v13
	v_add_u32_e32 v213, v3, v15
	v_mov_b32_e32 v214, 0x1000
	v_mov_b32_e32 v215, 0x1400
	s_barrier
	v_readlane_b32 s14, v251, 10
	v_readlane_b32 s15, v251, 11
	v_readlane_b32 s16, v251, 12
	v_readlane_b32 s17, v251, 13
	v_readlane_b32 s18, v251, 14
	v_readlane_b32 s19, v251, 15
	v_readlane_b32 s20, v251, 16
	v_readlane_b32 s21, v251, 17
	v_readlane_b32 s22, v251, 18
	v_readlane_b32 s23, v251, 19
	v_readlane_b32 s24, v251, 20
	v_readlane_b32 s25, v251, 21
	v_readlane_b32 s26, v251, 22
	v_readlane_b32 s27, v251, 23
	s_branch .LBB0_192

.LBB0_442:
	s_or_b64 exec, exec, s[14:15]
	s_waitcnt lgkmcnt(0)
	s_barrier
	ds_read_b128 v[46:49], v203 offset:50176
	ds_read_b128 v[54:57], v203 offset:51456
	v_add_u32_e32 v0, 0x400, v204
	ds_read_b128 v[66:69], v203 offset:52736
	ds_read_b128 v[122:125], v203 offset:54016
	v_add_u32_e32 v50, 0x2000, v204
	s_waitcnt lgkmcnt(3)
	v_mfma_f32_16x16x32_bf16 v[58:61], v[46:49], v[36:39], 0
	v_mfma_f32_16x16x32_bf16 v[46:49], v[46:49], v[16:19], 0
	s_nop 7
	ds_write2_b32 v204, v58, v46 offset1:16
	ds_write2_b32 v204, v59, v47 offset0:128 offset1:144
	ds_write2_b32 v0, v60, v48 offset1:16
	ds_write2_b32 v0, v61, v49 offset0:128 offset1:144
	s_waitcnt lgkmcnt(6)
	v_mfma_f32_16x16x32_bf16 v[62:65], v[54:57], v[36:39], 0
	v_add_u32_e32 v0, 0x2400, v204
	v_mfma_f32_16x16x32_bf16 v[46:49], v[54:57], v[16:19], 0
	s_nop 7
	ds_write2_b32 v50, v62, v46 offset1:16
	ds_write2_b32 v50, v63, v47 offset0:128 offset1:144
	s_waitcnt lgkmcnt(7)
	v_mfma_f32_16x16x32_bf16 v[54:57], v[66:69], v[36:39], 0
	ds_write2_b32 v0, v64, v48 offset1:16
	ds_write2_b32 v0, v65, v49 offset0:128 offset1:144
	v_add_u32_e32 v0, 0x4000, v204
	v_mfma_f32_16x16x32_bf16 v[46:49], v[66:69], v[16:19], 0
	s_nop 7
	ds_write2_b32 v0, v54, v46 offset1:16
	ds_write2_b32 v0, v55, v47 offset0:128 offset1:144
	v_add_u32_e32 v0, 0x4400, v204
	s_waitcnt lgkmcnt(10)
	v_mfma_f32_16x16x32_bf16 v[58:61], v[122:125], v[36:39], 0
	ds_write2_b32 v0, v56, v48 offset1:16
	ds_write2_b32 v0, v57, v49 offset0:128 offset1:144
	v_add_u32_e32 v0, 0x6000, v204
	v_mfma_f32_16x16x32_bf16 v[46:49], v[122:125], v[16:19], 0
	s_nop 7
	ds_write2_b32 v0, v58, v46 offset1:16
	ds_write2_b32 v0, v59, v47 offset0:128 offset1:144
	v_add_u32_e32 v0, 0x6400, v204
	ds_write2_b32 v0, v60, v48 offset1:16
	ds_write2_b32 v0, v61, v49 offset0:128 offset1:144
	s_waitcnt lgkmcnt(0)
	s_barrier
	s_and_saveexec_b64 s[14:15], s[10:11]
	s_cbranch_execz .LBB0_438
	v_xor_b32_e32 v253, 0x80, v97
	v_xor_b32_e32 v254, 0x100, v97
	v_xor_b32_e32 v255, 0x180, v97
	ds_read_b64 v[232:233], v97
	ds_read_b64 v[234:235], v97 offset:512
	ds_read_b64 v[236:237], v97 offset:1024
	ds_read_b64 v[238:239], v97 offset:1536
	ds_read_b64 v[240:241], v253 offset:2048
	ds_read_b64 v[242:243], v253 offset:2560
	ds_read_b64 v[244:245], v253 offset:3072
	ds_read_b64 v[246:247], v253 offset:3584
	ds_read_b64 v[54:55], v254 offset:4096
	ds_read_b64 v[56:57], v254 offset:4608
	ds_read_b64 v[58:59], v254 offset:5120
	ds_read_b64 v[60:61], v254 offset:5632
	ds_read_b64 v[62:63], v255 offset:6144
	ds_read_b64 v[64:65], v255 offset:6656
	ds_read_b64 v[46:47], v255 offset:7168
	s_waitcnt lgkmcnt(8)
	ds_read_b64 v[48:49], v255 offset:7680
	v_fma_f32 v50, -v52, v45, v232
	v_fma_f32 v51, v52, v44, v233
	v_fma_f32 v44, v2, v44, v50
	v_fma_f32 v45, v2, v45, v51
	v_cvt_pk_bf16_f32 v0, v44, v45
	ds_write_b32 v229, v0 offset:32768
	v_fma_f32 v50, -v52, v45, v234
	v_fma_f32 v51, v52, v44, v235
	v_fma_f32 v44, v2, v44, v50
	v_fma_f32 v45, v2, v45, v51
	v_cvt_pk_bf16_f32 v66, v44, v45
	ds_write_b32 v229, v66 offset:33040
	v_fma_f32 v50, -v52, v45, v236
	v_fma_f32 v51, v52, v44, v237
	v_fma_f32 v44, v2, v44, v50
	v_fma_f32 v45, v2, v45, v51
	v_cvt_pk_bf16_f32 v0, v44, v45
	ds_write_b32 v229, v0 offset:33312
	v_fma_f32 v50, -v52, v45, v238
	v_fma_f32 v51, v52, v44, v239
	v_fma_f32 v44, v2, v44, v50
	v_fma_f32 v45, v2, v45, v51
	v_cvt_pk_bf16_f32 v66, v44, v45
	ds_write_b32 v229, v66 offset:33584
	v_fma_f32 v50, -v52, v45, v240
	v_fma_f32 v51, v52, v44, v241
	v_fma_f32 v44, v2, v44, v50
	v_fma_f32 v45, v2, v45, v51
	v_cvt_pk_bf16_f32 v0, v44, v45
	ds_write_b32 v229, v0 offset:33856
	v_fma_f32 v50, -v52, v45, v242
	v_fma_f32 v51, v52, v44, v243
	v_fma_f32 v44, v2, v44, v50
	v_fma_f32 v45, v2, v45, v51
	v_cvt_pk_bf16_f32 v66, v44, v45
	ds_write_b32 v229, v66 offset:34128
	v_fma_f32 v50, -v52, v45, v244
	v_fma_f32 v51, v52, v44, v245
	v_fma_f32 v44, v2, v44, v50
	v_fma_f32 v45, v2, v45, v51
	v_cvt_pk_bf16_f32 v0, v44, v45
	s_waitcnt lgkmcnt(8)
	ds_write_b32 v229, v0 offset:34400
	v_fma_f32 v50, -v52, v45, v246
	v_fma_f32 v51, v52, v44, v247
	v_fma_f32 v44, v2, v44, v50
	v_fma_f32 v45, v2, v45, v51
	v_cvt_pk_bf16_f32 v66, v44, v45
	ds_write_b32 v229, v66 offset:34672
	ds_read_b64 v[232:233], v97 offset:8192
	ds_read_b64 v[234:235], v97 offset:8704
	ds_read_b64 v[236:237], v97 offset:9216
	ds_read_b64 v[238:239], v97 offset:9728
	ds_read_b64 v[240:241], v253 offset:10240
	s_waitcnt lgkmcnt(8)
	ds_read_b64 v[242:243], v253 offset:10752
	ds_read_b64 v[244:245], v253 offset:11264
	ds_read_b64 v[246:247], v253 offset:11776
	v_fma_f32 v50, -v52, v45, v54
	v_fma_f32 v51, v52, v44, v55
	v_fma_f32 v44, v2, v44, v50
	v_fma_f32 v45, v2, v45, v51
	v_cvt_pk_bf16_f32 v0, v44, v45
	ds_write_b32 v229, v0 offset:34944
	v_fma_f32 v50, -v52, v45, v56
	v_fma_f32 v51, v52, v44, v57
	v_fma_f32 v44, v2, v44, v50
	v_fma_f32 v45, v2, v45, v51
	v_cvt_pk_bf16_f32 v66, v44, v45
	ds_write_b32 v229, v66 offset:35216
	v_fma_f32 v50, -v52, v45, v58
	v_fma_f32 v51, v52, v44, v59
	v_fma_f32 v44, v2, v44, v50
	v_fma_f32 v45, v2, v45, v51
	v_cvt_pk_bf16_f32 v0, v44, v45
	ds_write_b32 v229, v0 offset:35488
	v_fma_f32 v50, -v52, v45, v60
	v_fma_f32 v51, v52, v44, v61
	v_fma_f32 v44, v2, v44, v50
	v_fma_f32 v45, v2, v45, v51
	v_cvt_pk_bf16_f32 v66, v44, v45
	ds_write_b32 v229, v66 offset:35760
	v_fma_f32 v50, -v52, v45, v62
	v_fma_f32 v51, v52, v44, v63
	v_fma_f32 v44, v2, v44, v50
	v_fma_f32 v45, v2, v45, v51
	v_cvt_pk_bf16_f32 v0, v44, v45
	s_waitcnt lgkmcnt(8)
	ds_write_b32 v229, v0 offset:36032
	v_fma_f32 v50, -v52, v45, v64
	v_fma_f32 v51, v52, v44, v65
	v_fma_f32 v44, v2, v44, v50
	v_fma_f32 v45, v2, v45, v51
	v_cvt_pk_bf16_f32 v66, v44, v45
	ds_write_b32 v229, v66 offset:36304
	v_fma_f32 v50, -v52, v45, v46
	v_fma_f32 v51, v52, v44, v47
	v_fma_f32 v44, v2, v44, v50
	v_fma_f32 v45, v2, v45, v51
	v_cvt_pk_bf16_f32 v0, v44, v45
	ds_write_b32 v229, v0 offset:36576
	v_fma_f32 v50, -v52, v45, v48
	v_fma_f32 v51, v52, v44, v49
	v_fma_f32 v44, v2, v44, v50
	v_fma_f32 v45, v2, v45, v51
	v_cvt_pk_bf16_f32 v66, v44, v45
	ds_write_b32 v229, v66 offset:36848
	ds_read_b64 v[54:55], v254 offset:12288
	ds_read_b64 v[56:57], v254 offset:12800
	ds_read_b64 v[58:59], v254 offset:13312
	s_waitcnt lgkmcnt(8)
	ds_read_b64 v[60:61], v254 offset:13824
	ds_read_b64 v[62:63], v255 offset:14336
	ds_read_b64 v[64:65], v255 offset:14848
	ds_read_b64 v[46:47], v255 offset:15360
	ds_read_b64 v[48:49], v255 offset:15872
	v_fma_f32 v50, -v52, v45, v232
	v_fma_f32 v51, v52, v44, v233
	v_fma_f32 v44, v2, v44, v50
	v_fma_f32 v45, v2, v45, v51
	v_cvt_pk_bf16_f32 v0, v44, v45
	ds_write_b32 v229, v0 offset:37120
	v_fma_f32 v50, -v52, v45, v234
	v_fma_f32 v51, v52, v44, v235
	v_fma_f32 v44, v2, v44, v50
	v_fma_f32 v45, v2, v45, v51
	v_cvt_pk_bf16_f32 v66, v44, v45
	ds_write_b32 v229, v66 offset:37392
	v_fma_f32 v50, -v52, v45, v236
	v_fma_f32 v51, v52, v44, v237
	v_fma_f32 v44, v2, v44, v50
	v_fma_f32 v45, v2, v45, v51
	v_cvt_pk_bf16_f32 v0, v44, v45
	s_waitcnt lgkmcnt(8)
	ds_write_b32 v229, v0 offset:37664
	v_fma_f32 v50, -v52, v45, v238
	v_fma_f32 v51, v52, v44, v239
	v_fma_f32 v44, v2, v44, v50
	v_fma_f32 v45, v2, v45, v51
	v_cvt_pk_bf16_f32 v66, v44, v45
	ds_write_b32 v229, v66 offset:37936
	v_fma_f32 v50, -v52, v45, v240
	v_fma_f32 v51, v52, v44, v241
	v_fma_f32 v44, v2, v44, v50
	v_fma_f32 v45, v2, v45, v51
	v_cvt_pk_bf16_f32 v0, v44, v45
	ds_write_b32 v229, v0 offset:38208
	v_fma_f32 v50, -v52, v45, v242
	v_fma_f32 v51, v52, v44, v243
	v_fma_f32 v44, v2, v44, v50
	v_fma_f32 v45, v2, v45, v51
	v_cvt_pk_bf16_f32 v66, v44, v45
	ds_write_b32 v229, v66 offset:38480
	v_fma_f32 v50, -v52, v45, v244
	v_fma_f32 v51, v52, v44, v245
	v_fma_f32 v44, v2, v44, v50
	v_fma_f32 v45, v2, v45, v51
	v_cvt_pk_bf16_f32 v0, v44, v45
	ds_write_b32 v229, v0 offset:38752
	v_fma_f32 v50, -v52, v45, v246
	v_fma_f32 v51, v52, v44, v247
	v_fma_f32 v44, v2, v44, v50
	v_fma_f32 v45, v2, v45, v51
	v_cvt_pk_bf16_f32 v66, v44, v45
	ds_write_b32 v229, v66 offset:39024
	ds_read_b64 v[232:233], v97 offset:16384
	s_waitcnt lgkmcnt(8)
	ds_read_b64 v[234:235], v97 offset:16896
	ds_read_b64 v[236:237], v97 offset:17408
	ds_read_b64 v[238:239], v97 offset:17920
	ds_read_b64 v[240:241], v253 offset:18432
	ds_read_b64 v[242:243], v253 offset:18944
	ds_read_b64 v[244:245], v253 offset:19456
	ds_read_b64 v[246:247], v253 offset:19968
	v_fma_f32 v50, -v52, v45, v54
	v_fma_f32 v51, v52, v44, v55
	v_fma_f32 v44, v2, v44, v50
	v_fma_f32 v45, v2, v45, v51
	v_cvt_pk_bf16_f32 v0, v44, v45
	s_waitcnt lgkmcnt(8)
	ds_write_b32 v229, v0 offset:39296
	v_fma_f32 v50, -v52, v45, v56
	v_fma_f32 v51, v52, v44, v57
	v_fma_f32 v44, v2, v44, v50
	v_fma_f32 v45, v2, v45, v51
	v_cvt_pk_bf16_f32 v66, v44, v45
	ds_write_b32 v229, v66 offset:39568
	v_fma_f32 v50, -v52, v45, v58
	v_fma_f32 v51, v52, v44, v59
	v_fma_f32 v44, v2, v44, v50
	v_fma_f32 v45, v2, v45, v51
	v_cvt_pk_bf16_f32 v0, v44, v45
	ds_write_b32 v229, v0 offset:39840
	v_fma_f32 v50, -v52, v45, v60
	v_fma_f32 v51, v52, v44, v61
	v_fma_f32 v44, v2, v44, v50
	v_fma_f32 v45, v2, v45, v51
	v_cvt_pk_bf16_f32 v66, v44, v45
	ds_write_b32 v229, v66 offset:40112
	v_fma_f32 v50, -v52, v45, v62
	v_fma_f32 v51, v52, v44, v63
	v_fma_f32 v44, v2, v44, v50
	v_fma_f32 v45, v2, v45, v51
	v_cvt_pk_bf16_f32 v0, v44, v45
	ds_write_b32 v229, v0 offset:40384
	v_fma_f32 v50, -v52, v45, v64
	v_fma_f32 v51, v52, v44, v65
	v_fma_f32 v44, v2, v44, v50
	v_fma_f32 v45, v2, v45, v51
	v_cvt_pk_bf16_f32 v66, v44, v45
	ds_write_b32 v229, v66 offset:40656
	v_fma_f32 v50, -v52, v45, v46
	v_fma_f32 v51, v52, v44, v47
	v_fma_f32 v44, v2, v44, v50
	v_fma_f32 v45, v2, v45, v51
	v_cvt_pk_bf16_f32 v0, v44, v45
	ds_write_b32 v229, v0 offset:40928
	v_fma_f32 v50, -v52, v45, v48
	v_fma_f32 v51, v52, v44, v49
	v_fma_f32 v44, v2, v44, v50
	v_fma_f32 v45, v2, v45, v51
	v_cvt_pk_bf16_f32 v66, v44, v45
	s_waitcnt lgkmcnt(8)
	ds_write_b32 v229, v66 offset:41200
	ds_read_b64 v[54:55], v254 offset:20480
	ds_read_b64 v[56:57], v254 offset:20992
	ds_read_b64 v[58:59], v254 offset:21504
	ds_read_b64 v[60:61], v254 offset:22016
	ds_read_b64 v[62:63], v255 offset:22528
	ds_read_b64 v[64:65], v255 offset:23040
	s_waitcnt lgkmcnt(8)
	ds_read_b64 v[46:47], v255 offset:23552
	ds_read_b64 v[48:49], v255 offset:24064
	v_fma_f32 v50, -v52, v45, v232
	v_fma_f32 v51, v52, v44, v233
	v_fma_f32 v44, v2, v44, v50
	v_fma_f32 v45, v2, v45, v51
	v_cvt_pk_bf16_f32 v0, v44, v45
	ds_write_b32 v229, v0 offset:41472
	v_fma_f32 v50, -v52, v45, v234
	v_fma_f32 v51, v52, v44, v235
	v_fma_f32 v44, v2, v44, v50
	v_fma_f32 v45, v2, v45, v51
	v_cvt_pk_bf16_f32 v66, v44, v45
	ds_write_b32 v229, v66 offset:41744
	v_fma_f32 v50, -v52, v45, v236
	v_fma_f32 v51, v52, v44, v237
	v_fma_f32 v44, v2, v44, v50
	v_fma_f32 v45, v2, v45, v51
	v_cvt_pk_bf16_f32 v0, v44, v45
	ds_write_b32 v229, v0 offset:42016
	v_fma_f32 v50, -v52, v45, v238
	v_fma_f32 v51, v52, v44, v239
	v_fma_f32 v44, v2, v44, v50
	v_fma_f32 v45, v2, v45, v51
	v_cvt_pk_bf16_f32 v66, v44, v45
	ds_write_b32 v229, v66 offset:42288
	v_fma_f32 v50, -v52, v45, v240
	v_fma_f32 v51, v52, v44, v241
	v_fma_f32 v44, v2, v44, v50
	v_fma_f32 v45, v2, v45, v51
	v_cvt_pk_bf16_f32 v0, v44, v45
	ds_write_b32 v229, v0 offset:42560
	v_fma_f32 v50, -v52, v45, v242
	v_fma_f32 v51, v52, v44, v243
	v_fma_f32 v44, v2, v44, v50
	v_fma_f32 v45, v2, v45, v51
	v_cvt_pk_bf16_f32 v66, v44, v45
	s_waitcnt lgkmcnt(8)
	ds_write_b32 v229, v66 offset:42832
	v_fma_f32 v50, -v52, v45, v244
	v_fma_f32 v51, v52, v44, v245
	v_fma_f32 v44, v2, v44, v50
	v_fma_f32 v45, v2, v45, v51
	v_cvt_pk_bf16_f32 v0, v44, v45
	ds_write_b32 v229, v0 offset:43104
	v_fma_f32 v50, -v52, v45, v246
	v_fma_f32 v51, v52, v44, v247
	v_fma_f32 v44, v2, v44, v50
	v_fma_f32 v45, v2, v45, v51
	v_cvt_pk_bf16_f32 v66, v44, v45
	ds_write_b32 v229, v66 offset:43376
	ds_read_b64 v[232:233], v97 offset:24576
	ds_read_b64 v[234:235], v97 offset:25088
	ds_read_b64 v[236:237], v97 offset:25600
	ds_read_b64 v[238:239], v97 offset:26112
	s_waitcnt lgkmcnt(8)
	ds_read_b64 v[240:241], v253 offset:26624
	ds_read_b64 v[242:243], v253 offset:27136
	ds_read_b64 v[244:245], v253 offset:27648
	ds_read_b64 v[246:247], v253 offset:28160
	v_fma_f32 v50, -v52, v45, v54
	v_fma_f32 v51, v52, v44, v55
	v_fma_f32 v44, v2, v44, v50
	v_fma_f32 v45, v2, v45, v51
	v_cvt_pk_bf16_f32 v0, v44, v45
	ds_write_b32 v229, v0 offset:43648
	v_fma_f32 v50, -v52, v45, v56
	v_fma_f32 v51, v52, v44, v57
	v_fma_f32 v44, v2, v44, v50
	v_fma_f32 v45, v2, v45, v51
	v_cvt_pk_bf16_f32 v66, v44, v45
	ds_write_b32 v229, v66 offset:43920
	v_fma_f32 v50, -v52, v45, v58
	v_fma_f32 v51, v52, v44, v59
	v_fma_f32 v44, v2, v44, v50
	v_fma_f32 v45, v2, v45, v51
	v_cvt_pk_bf16_f32 v0, v44, v45
	ds_write_b32 v229, v0 offset:44192
	v_fma_f32 v50, -v52, v45, v60
	v_fma_f32 v51, v52, v44, v61
	v_fma_f32 v44, v2, v44, v50
	v_fma_f32 v45, v2, v45, v51
	v_cvt_pk_bf16_f32 v66, v44, v45
	s_waitcnt lgkmcnt(8)
	ds_write_b32 v229, v66 offset:44464
	v_fma_f32 v50, -v52, v45, v62
	v_fma_f32 v51, v52, v44, v63
	v_fma_f32 v44, v2, v44, v50
	v_fma_f32 v45, v2, v45, v51
	v_cvt_pk_bf16_f32 v0, v44, v45
	ds_write_b32 v229, v0 offset:44736
	v_fma_f32 v50, -v52, v45, v64
	v_fma_f32 v51, v52, v44, v65
	v_fma_f32 v44, v2, v44, v50
	v_fma_f32 v45, v2, v45, v51
	v_cvt_pk_bf16_f32 v66, v44, v45
	ds_write_b32 v229, v66 offset:45008
	v_fma_f32 v50, -v52, v45, v46
	v_fma_f32 v51, v52, v44, v47
	v_fma_f32 v44, v2, v44, v50
	v_fma_f32 v45, v2, v45, v51
	v_cvt_pk_bf16_f32 v0, v44, v45
	ds_write_b32 v229, v0 offset:45280
	v_fma_f32 v50, -v52, v45, v48
	v_fma_f32 v51, v52, v44, v49
	v_fma_f32 v44, v2, v44, v50
	v_fma_f32 v45, v2, v45, v51
	v_cvt_pk_bf16_f32 v66, v44, v45
	ds_write_b32 v229, v66 offset:45552
	ds_read_b64 v[54:55], v254 offset:28672
	ds_read_b64 v[56:57], v254 offset:29184
	s_waitcnt lgkmcnt(8)
	ds_read_b64 v[58:59], v254 offset:29696
	ds_read_b64 v[60:61], v254 offset:30208
	ds_read_b64 v[62:63], v255 offset:30720
	ds_read_b64 v[64:65], v255 offset:31232
	ds_read_b64 v[46:47], v255 offset:31744
	ds_read_b64 v[48:49], v255 offset:32256
	v_fma_f32 v50, -v52, v45, v232
	v_fma_f32 v51, v52, v44, v233
	v_fma_f32 v44, v2, v44, v50
	v_fma_f32 v45, v2, v45, v51
	v_cvt_pk_bf16_f32 v0, v44, v45
	ds_write_b32 v229, v0 offset:45824
	v_fma_f32 v50, -v52, v45, v234
	v_fma_f32 v51, v52, v44, v235
	v_fma_f32 v44, v2, v44, v50
	v_fma_f32 v45, v2, v45, v51
	v_cvt_pk_bf16_f32 v66, v44, v45
	s_waitcnt lgkmcnt(8)
	ds_write_b32 v229, v66 offset:46096
	v_fma_f32 v50, -v52, v45, v236
	v_fma_f32 v51, v52, v44, v237
	v_fma_f32 v44, v2, v44, v50
	v_fma_f32 v45, v2, v45, v51
	v_cvt_pk_bf16_f32 v0, v44, v45
	ds_write_b32 v229, v0 offset:46368
	v_fma_f32 v50, -v52, v45, v238
	v_fma_f32 v51, v52, v44, v239
	v_fma_f32 v44, v2, v44, v50
	v_fma_f32 v45, v2, v45, v51
	v_cvt_pk_bf16_f32 v66, v44, v45
	ds_write_b32 v229, v66 offset:46640
	v_fma_f32 v50, -v52, v45, v240
	v_fma_f32 v51, v52, v44, v241
	v_fma_f32 v44, v2, v44, v50
	v_fma_f32 v45, v2, v45, v51
	v_cvt_pk_bf16_f32 v0, v44, v45
	ds_write_b32 v229, v0 offset:46912
	v_fma_f32 v50, -v52, v45, v242
	v_fma_f32 v51, v52, v44, v243
	v_fma_f32 v44, v2, v44, v50
	v_fma_f32 v45, v2, v45, v51
	v_cvt_pk_bf16_f32 v66, v44, v45
	ds_write_b32 v229, v66 offset:47184
	v_fma_f32 v50, -v52, v45, v244
	v_fma_f32 v51, v52, v44, v245
	v_fma_f32 v44, v2, v44, v50
	v_fma_f32 v45, v2, v45, v51
	v_cvt_pk_bf16_f32 v0, v44, v45
	ds_write_b32 v229, v0 offset:47456
	v_fma_f32 v50, -v52, v45, v246
	v_fma_f32 v51, v52, v44, v247
	v_fma_f32 v44, v2, v44, v50
	v_fma_f32 v45, v2, v45, v51
	v_cvt_pk_bf16_f32 v66, v44, v45
	ds_write_b32 v229, v66 offset:47728
	v_fma_f32 v50, -v52, v45, v54
	v_fma_f32 v51, v52, v44, v55
	v_fma_f32 v44, v2, v44, v50
	v_fma_f32 v45, v2, v45, v51
	v_cvt_pk_bf16_f32 v0, v44, v45
	s_waitcnt lgkmcnt(8)
	ds_write_b32 v229, v0 offset:48000
	v_fma_f32 v50, -v52, v45, v56
	v_fma_f32 v51, v52, v44, v57
	v_fma_f32 v44, v2, v44, v50
	v_fma_f32 v45, v2, v45, v51
	v_cvt_pk_bf16_f32 v66, v44, v45
	ds_write_b32 v229, v66 offset:48272
	v_fma_f32 v50, -v52, v45, v58
	v_fma_f32 v51, v52, v44, v59
	v_fma_f32 v44, v2, v44, v50
	v_fma_f32 v45, v2, v45, v51
	v_cvt_pk_bf16_f32 v0, v44, v45
	ds_write_b32 v229, v0 offset:48544
	v_fma_f32 v50, -v52, v45, v60
	v_fma_f32 v51, v52, v44, v61
	v_fma_f32 v44, v2, v44, v50
	v_fma_f32 v45, v2, v45, v51
	v_cvt_pk_bf16_f32 v66, v44, v45
	ds_write_b32 v229, v66 offset:48816
	v_fma_f32 v50, -v52, v45, v62
	v_fma_f32 v51, v52, v44, v63
	v_fma_f32 v44, v2, v44, v50
	v_fma_f32 v45, v2, v45, v51
	v_cvt_pk_bf16_f32 v0, v44, v45
	ds_write_b32 v229, v0 offset:49088
	v_fma_f32 v50, -v52, v45, v64
	v_fma_f32 v51, v52, v44, v65
	v_fma_f32 v44, v2, v44, v50
	v_fma_f32 v45, v2, v45, v51
	v_cvt_pk_bf16_f32 v66, v44, v45
	ds_write_b32 v229, v66 offset:49360
	v_fma_f32 v50, -v52, v45, v46
	v_fma_f32 v51, v52, v44, v47
	v_fma_f32 v44, v2, v44, v50
	v_fma_f32 v45, v2, v45, v51
	v_cvt_pk_bf16_f32 v0, v44, v45
	ds_write_b32 v229, v0 offset:49632
	v_fma_f32 v50, -v52, v45, v48
	v_fma_f32 v51, v52, v44, v49
	v_fma_f32 v44, v2, v44, v50
	v_fma_f32 v45, v2, v45, v51
	v_cvt_pk_bf16_f32 v66, v44, v45
	s_waitcnt lgkmcnt(8)
	ds_write_b32 v229, v66 offset:49904
	s_branch .LBB0_438
